# merged-phase K-loop with LDS-DMA issued before the fragment reads in each load segment
# baseline (speedup 1.0000x reference)
; #define PG8_STAGE(bufoff, gbase, voff) do { _Pragma("unroll") for (int _i = 0; _i < 2; ++_i) \
;         __builtin_amdgcn_global_load_lds((const unsigned*)((const char*)(gbase) + (voff)[_i]), (LAS unsigned*)(lds + (bufoff) + ldsw + _i * 8192), 16, 0, 0); } while (0)
; #define PG8_LDA(dst, b, h) do { _Pragma("unroll") for (int m = 0; m < 4; ++m) _Pragma("unroll") for (int k = 0; k < 2; ++k) dst[m][k] = *(const LAS bf16x8*)(lds + PG8_SA(b, h) + aoff + m * 2048 + k * 1024); } while (0)
; #define PG8_LDB(dst, b, h) do { _Pragma("unroll") for (int n = 0; n < 2; ++n) _Pragma("unroll") for (int k = 0; k < 2; ++k) dst[n][k] = *(const LAS bf16x8*)(lds + PG8_SB(b, h) + boff + n * 2048 + k * 1024); } while (0)
; #define PG8_MMA(ai, bj, At, Bt) do { __builtin_amdgcn_s_setprio(1); _Pragma("unroll") for (int m = 0; m < 4; ++m) _Pragma("unroll") for (int n = 0; n < 2; ++n) _Pragma("unroll") for (int k = 0; k < 2; ++k) \
;         acc[ai][bj][m][n] = __builtin_amdgcn_mfma_f32_16x16x32_bf16(Bt[n][k], At[m][k], acc[ai][bj][m][n], 0, 0, 0); __builtin_amdgcn_s_setprio(0); } while (0)
; #define PG8_WAIT_L(n) asm volatile("s_waitcnt lgkmcnt(" #n ")" ::: "memory")
; #define PG8_BAR __builtin_amdgcn_s_barrier()
; #define PG8_SCHED __builtin_amdgcn_sched_barrier(0)
; __device__ __forceinline__ void gemm_phase(LAS unsigned char* lds, const Gemm g, const StaticOrder& S, const Epi& E) {
;     ...
;         for (int t = 0; t < nt; t += 2) {
;             const bool last = (t == nt - 2);
;             const char* a1 = cA + (size_t)(t + 1) * kstep;
;             const char* a2 = last ? nA : cA + (size_t)(t + 2) * kstep; const char* b2 = last ? nB : cB + (size_t)(t + 2) * kstep;
;             const char* a3 = a2 + kstep; const char* b3 = b2 + kstep;
;             PG8_LDB(B0, 0, 0); PG8_SCHED; PG8_LDA(At, 0, 0); PG8_STAGE(PG8_SA(1, 1), a1 + hstep, voffA);
;             PG8_WAIT_L(8); PG8_BAR; PG8_WAIT_L(0); PG8_MMA(0, 0, At, B0); PG8_BAR; PG8_SCHED;
;             PG8_LDB(B1, 0, 1); PG8_STAGE(PG8_SB(0, 0), b2, voffB);
;             PG8_BAR; PG8_WAIT_L(0); PG8_MMA(0, 1, At, B1); PG8_BAR;
;             PG8_LDA(At, 0, 1); PG8_STAGE(PG8_SA(0, 0), a2, voffA);
;             PG8_BAR; PG8_WAIT_L(0); PG8_MMA(1, 0, At, B0); PG8_BAR; PG8_SCHED;
;             PG8_STAGE(PG8_SB(0, 1), b2 + hstep, voffB);
.LBB0_555:
	s_add_i32 s61, s54, 2
	s_add_u32 s56, s44, 0x80
	s_addc_u32 s55, s45, 0
	s_cmp_eq_u32 s73, s54
	s_cselect_b32 s54, s28, s56
	s_cselect_b32 s55, s29, s55
	s_cselect_b32 s57, s47, s60
	s_cselect_b32 s56, s46, s59
	s_add_u32 s86, s59, s48
	s_addc_u32 s87, s60, 0
	s_sub_u32 s86, s86, 0x80
	s_subb_u32 s87, s87, 0
	v_add_u32_e32 v142, 0x10000, v244
	v_add_u32_e32 v178, 0x14000, v244
	s_waitcnt lgkmcnt(0)
	s_add_i32 m0, s65, 0x1c000
	s_nop 0
	global_load_lds_dwordx4 v182, s[86:87]
	s_add_i32 m0, s65, 0x1e000
	s_nop 0
	global_load_lds_dwordx4 v186, s[86:87]
	s_add_i32 m0, s66, 0xc000
	s_nop 0
	global_load_lds_dwordx4 v198, s[44:45]
	s_add_i32 m0, s66, 0xe000
	s_nop 0
	global_load_lds_dwordx4 v200, s[44:45]
	ds_read_b128 v[130:133], v142
	ds_read_b128 v[134:137], v142 offset:1024
	ds_read_b128 v[138:141], v142 offset:2048
	ds_read_b128 v[142:145], v142 offset:3072
	ds_read_b128 v[146:149], v245
	ds_read_b128 v[150:153], v245 offset:1024
	ds_read_b128 v[154:157], v245 offset:2048
	ds_read_b128 v[158:161], v245 offset:3072
	ds_read_b128 v[162:165], v245 offset:4096
	ds_read_b128 v[166:169], v245 offset:5120
	ds_read_b128 v[170:173], v245 offset:6144
	ds_read_b128 v[174:177], v245 offset:7168
	s_waitcnt lgkmcnt(8)
	ds_read_b128 v[202:205], v178
	ds_read_b128 v[206:209], v178 offset:1024
	ds_read_b128 v[210:213], v178 offset:2048
	ds_read_b128 v[214:217], v178 offset:3072
	s_cmp_eq_u32 s61, 2
	s_cbranch_scc1 .Lmy_q10_first
	s_waitcnt vmcnt(8)
.Lmy_q10_first:
	s_waitcnt lgkmcnt(4)
	s_barrier
	s_setprio 1
	v_mfma_f32_16x16x32_bf16 v[126:129], v[130:133], v[146:149], v[126:129]
	v_mfma_f32_16x16x32_bf16 v[122:125], v[138:141], v[146:149], v[122:125]
	v_mfma_f32_16x16x32_bf16 v[118:121], v[130:133], v[154:157], v[118:121]
	v_mfma_f32_16x16x32_bf16 v[110:113], v[138:141], v[154:157], v[110:113]
	v_mfma_f32_16x16x32_bf16 v[102:105], v[130:133], v[162:165], v[102:105]
	v_mfma_f32_16x16x32_bf16 v[94:97], v[138:141], v[162:165], v[94:97]
	v_mfma_f32_16x16x32_bf16 v[86:89], v[130:133], v[170:173], v[86:89]
	v_mfma_f32_16x16x32_bf16 v[78:81], v[138:141], v[170:173], v[78:81]
	v_mfma_f32_16x16x32_bf16 v[126:129], v[134:137], v[150:153], v[126:129]
	v_mfma_f32_16x16x32_bf16 v[122:125], v[142:145], v[150:153], v[122:125]
	v_mfma_f32_16x16x32_bf16 v[118:121], v[134:137], v[158:161], v[118:121]
	v_mfma_f32_16x16x32_bf16 v[110:113], v[142:145], v[158:161], v[110:113]
	v_mfma_f32_16x16x32_bf16 v[102:105], v[134:137], v[166:169], v[102:105]
	v_mfma_f32_16x16x32_bf16 v[94:97], v[142:145], v[166:169], v[94:97]
	v_mfma_f32_16x16x32_bf16 v[86:89], v[134:137], v[174:177], v[86:89]
	v_mfma_f32_16x16x32_bf16 v[78:81], v[142:145], v[174:177], v[78:81]
	s_waitcnt lgkmcnt(0)
	v_mfma_f32_16x16x32_bf16 v[114:117], v[202:205], v[146:149], v[114:117]
	v_mfma_f32_16x16x32_bf16 v[106:109], v[210:213], v[146:149], v[106:109]
	v_mfma_f32_16x16x32_bf16 v[98:101], v[202:205], v[154:157], v[98:101]
	v_mfma_f32_16x16x32_bf16 v[90:93], v[210:213], v[154:157], v[90:93]
	v_mfma_f32_16x16x32_bf16 v[82:85], v[202:205], v[162:165], v[82:85]
	v_mfma_f32_16x16x32_bf16 v[74:77], v[210:213], v[162:165], v[74:77]
	v_mfma_f32_16x16x32_bf16 v[70:73], v[202:205], v[170:173], v[70:73]
	v_mfma_f32_16x16x32_bf16 v[66:69], v[210:213], v[170:173], v[66:69]
	v_mfma_f32_16x16x32_bf16 v[114:117], v[206:209], v[150:153], v[114:117]
	v_mfma_f32_16x16x32_bf16 v[106:109], v[214:217], v[150:153], v[106:109]
	v_mfma_f32_16x16x32_bf16 v[98:101], v[206:209], v[158:161], v[98:101]
	v_mfma_f32_16x16x32_bf16 v[90:93], v[214:217], v[158:161], v[90:93]
	v_mfma_f32_16x16x32_bf16 v[82:85], v[206:209], v[166:169], v[82:85]
	v_mfma_f32_16x16x32_bf16 v[74:77], v[214:217], v[166:169], v[74:77]
	v_mfma_f32_16x16x32_bf16 v[70:73], v[206:209], v[174:177], v[70:73]
	v_mfma_f32_16x16x32_bf16 v[66:69], v[214:217], v[174:177], v[66:69]
	s_setprio 0
	s_barrier
	s_add_u32 s86, s56, 0x80
	s_addc_u32 s87, s57, 0
	s_add_u32 s88, s54, 0x80
	s_addc_u32 s89, s55, 0
	s_add_i32 m0, s65, 0x10000
	s_nop 0
	global_load_lds_dwordx4 v182, s[56:57]
	s_add_i32 m0, s65, 0x12000
	s_nop 0
	global_load_lds_dwordx4 v186, s[56:57]
	s_mov_b32 m0, s66
	s_nop 0
	global_load_lds_dwordx4 v180, s[54:55]
	s_mov_b32 m0, s67
	s_nop 0
	global_load_lds_dwordx4 v184, s[54:55]
	ds_read_b128 v[146:149], v245 offset:16384
	ds_read_b128 v[150:153], v245 offset:17408
	ds_read_b128 v[154:157], v245 offset:18432
	ds_read_b128 v[158:161], v245 offset:19456
	ds_read_b128 v[162:165], v245 offset:20480
	ds_read_b128 v[166:169], v245 offset:21504
	ds_read_b128 v[170:173], v245 offset:22528
	ds_read_b128 v[174:177], v245 offset:23552
	s_waitcnt vmcnt(6) lgkmcnt(0)
	s_barrier
; #define PG8_STAGE(bufoff, gbase, voff) do { _Pragma("unroll") for (int _i = 0; _i < 2; ++_i) \
;         __builtin_amdgcn_global_load_lds((const unsigned*)((const char*)(gbase) + (voff)[_i]), (LAS unsigned*)(lds + (bufoff) + ldsw + _i * 8192), 16, 0, 0); } while (0)
; #define PG8_LDA(dst, b, h) do { _Pragma("unroll") for (int m = 0; m < 4; ++m) _Pragma("unroll") for (int k = 0; k < 2; ++k) dst[m][k] = *(const LAS bf16x8*)(lds + PG8_SA(b, h) + aoff + m * 2048 + k * 1024); } while (0)
; #define PG8_LDB(dst, b, h) do { _Pragma("unroll") for (int n = 0; n < 2; ++n) _Pragma("unroll") for (int k = 0; k < 2; ++k) dst[n][k] = *(const LAS bf16x8*)(lds + PG8_SB(b, h) + boff + n * 2048 + k * 1024); } while (0)
; #define PG8_MMA(ai, bj, At, Bt) do { __builtin_amdgcn_s_setprio(1); _Pragma("unroll") for (int m = 0; m < 4; ++m) _Pragma("unroll") for (int n = 0; n < 2; ++n) _Pragma("unroll") for (int k = 0; k < 2; ++k) \
;         acc[ai][bj][m][n] = __builtin_amdgcn_mfma_f32_16x16x32_bf16(Bt[n][k], At[m][k], acc[ai][bj][m][n], 0, 0, 0); __builtin_amdgcn_s_setprio(0); } while (0)
; #define PG8_WAIT_V(n) asm volatile("s_waitcnt vmcnt(" #n ")" ::: "memory")
; #define PG8_WAIT_L(n) asm volatile("s_waitcnt lgkmcnt(" #n ")" ::: "memory")
; #define PG8_BAR __builtin_amdgcn_s_barrier()
; #define PG8_SCHED __builtin_amdgcn_sched_barrier(0)
; __device__ __forceinline__ void gemm_phase(LAS unsigned char* lds, const Gemm g, const StaticOrder& S, const Epi& E) {
;     ...
;             PG8_BAR; PG8_WAIT_L(0); PG8_MMA(1, 0, At, B0); PG8_BAR; PG8_SCHED;
;             PG8_STAGE(PG8_SB(0, 1), b2 + hstep, voffB);
;             PG8_WAIT_V(6); PG8_BAR; PG8_MMA(1, 1, At, B1); PG8_BAR;
;             PG8_LDB(B0, 1, 0); PG8_SCHED; PG8_LDA(At, 1, 0); PG8_STAGE(PG8_SA(0, 1), a2 + hstep, voffA);
;             PG8_WAIT_L(8); PG8_BAR; PG8_WAIT_L(0); PG8_MMA(0, 0, At, B0); PG8_BAR; PG8_SCHED;
;             PG8_LDB(B1, 1, 1); PG8_STAGE(PG8_SB(1, 0), b3, voffB);
;             PG8_BAR; PG8_WAIT_L(0); PG8_MMA(0, 1, At, B1); PG8_BAR;
;             PG8_LDA(At, 1, 1); PG8_STAGE(PG8_SA(1, 0), a3, voffA);
;             PG8_BAR; PG8_WAIT_L(0); PG8_MMA(1, 0, At, B0); PG8_BAR; PG8_SCHED;
;             PG8_STAGE(PG8_SB(1, 1), b3 + hstep, voffB);
;             PG8_WAIT_V(6); PG8_BAR; PG8_MMA(1, 1, At, B1); PG8_BAR;
	s_setprio 1
	v_mfma_f32_16x16x32_bf16 v[62:65], v[130:133], v[146:149], v[62:65]
	v_mfma_f32_16x16x32_bf16 v[58:61], v[138:141], v[146:149], v[58:61]
	v_mfma_f32_16x16x32_bf16 v[54:57], v[130:133], v[154:157], v[54:57]
	v_mfma_f32_16x16x32_bf16 v[50:53], v[138:141], v[154:157], v[50:53]
	v_mfma_f32_16x16x32_bf16 v[38:41], v[130:133], v[162:165], v[38:41]
	v_mfma_f32_16x16x32_bf16 v[34:37], v[138:141], v[162:165], v[34:37]
	v_mfma_f32_16x16x32_bf16 v[22:25], v[130:133], v[170:173], v[22:25]
	v_mfma_f32_16x16x32_bf16 v[18:21], v[138:141], v[170:173], v[18:21]
	v_mfma_f32_16x16x32_bf16 v[62:65], v[134:137], v[150:153], v[62:65]
	v_mfma_f32_16x16x32_bf16 v[58:61], v[142:145], v[150:153], v[58:61]
	v_mfma_f32_16x16x32_bf16 v[54:57], v[134:137], v[158:161], v[54:57]
	v_mfma_f32_16x16x32_bf16 v[50:53], v[142:145], v[158:161], v[50:53]
	v_mfma_f32_16x16x32_bf16 v[38:41], v[134:137], v[166:169], v[38:41]
	v_mfma_f32_16x16x32_bf16 v[34:37], v[142:145], v[166:169], v[34:37]
	v_mfma_f32_16x16x32_bf16 v[22:25], v[134:137], v[174:177], v[22:25]
	v_mfma_f32_16x16x32_bf16 v[18:21], v[142:145], v[174:177], v[18:21]
	v_mfma_f32_16x16x32_bf16 v[46:49], v[202:205], v[146:149], v[46:49]
	v_mfma_f32_16x16x32_bf16 v[42:45], v[210:213], v[146:149], v[42:45]
	v_mfma_f32_16x16x32_bf16 v[30:33], v[202:205], v[154:157], v[30:33]
	v_mfma_f32_16x16x32_bf16 v[26:29], v[210:213], v[154:157], v[26:29]
	v_mfma_f32_16x16x32_bf16 v[14:17], v[202:205], v[162:165], v[14:17]
	v_mfma_f32_16x16x32_bf16 v[10:13], v[210:213], v[162:165], v[10:13]
	v_mfma_f32_16x16x32_bf16 v[6:9], v[202:205], v[170:173], v[6:9]
	v_mfma_f32_16x16x32_bf16 v[2:5], v[210:213], v[170:173], v[2:5]
	v_mfma_f32_16x16x32_bf16 v[46:49], v[206:209], v[150:153], v[46:49]
	v_mfma_f32_16x16x32_bf16 v[42:45], v[214:217], v[150:153], v[42:45]
	v_mfma_f32_16x16x32_bf16 v[30:33], v[206:209], v[158:161], v[30:33]
	v_mfma_f32_16x16x32_bf16 v[26:29], v[214:217], v[158:161], v[26:29]
	v_mfma_f32_16x16x32_bf16 v[14:17], v[206:209], v[166:169], v[14:17]
	v_mfma_f32_16x16x32_bf16 v[10:13], v[214:217], v[166:169], v[10:13]
	v_mfma_f32_16x16x32_bf16 v[6:9], v[206:209], v[174:177], v[6:9]
	v_mfma_f32_16x16x32_bf16 v[2:5], v[214:217], v[174:177], v[2:5]
	s_setprio 0
	s_barrier
	s_add_u32 s56, s56, s48
	s_addc_u32 s57, s57, 0
	s_add_u32 s54, s54, s48
	s_addc_u32 s55, s55, 0
	v_add_u32_e32 v142, 0x18000, v244
	v_add_u32_e32 v178, 0x1c000, v244
	s_add_i32 m0, s65, 0x14000
	s_nop 0
	global_load_lds_dwordx4 v182, s[56:57]
	s_add_i32 m0, s65, 0x16000
	s_nop 0
	global_load_lds_dwordx4 v186, s[56:57]
	s_mov_b32 m0, s68
	s_nop 0
	global_load_lds_dwordx4 v180, s[54:55]
	s_mov_b32 m0, s69
	s_nop 0
	global_load_lds_dwordx4 v184, s[54:55]
	ds_read_b128 v[130:133], v142
	ds_read_b128 v[134:137], v142 offset:1024
	ds_read_b128 v[138:141], v142 offset:2048
	ds_read_b128 v[142:145], v142 offset:3072
	ds_read_b128 v[146:149], v245 offset:32768
	ds_read_b128 v[150:153], v245 offset:33792
	ds_read_b128 v[154:157], v245 offset:34816
	ds_read_b128 v[158:161], v245 offset:35840
	ds_read_b128 v[162:165], v245 offset:36864
	ds_read_b128 v[166:169], v245 offset:37888
	ds_read_b128 v[170:173], v245 offset:38912
	ds_read_b128 v[174:177], v245 offset:39936
	s_waitcnt lgkmcnt(8)
	ds_read_b128 v[202:205], v178
	ds_read_b128 v[206:209], v178 offset:1024
	ds_read_b128 v[210:213], v178 offset:2048
	ds_read_b128 v[214:217], v178 offset:3072
	s_waitcnt vmcnt(8) lgkmcnt(4)
	s_barrier
	s_setprio 1
	v_mfma_f32_16x16x32_bf16 v[126:129], v[130:133], v[146:149], v[126:129]
	v_mfma_f32_16x16x32_bf16 v[122:125], v[138:141], v[146:149], v[122:125]
	v_mfma_f32_16x16x32_bf16 v[118:121], v[130:133], v[154:157], v[118:121]
	v_mfma_f32_16x16x32_bf16 v[110:113], v[138:141], v[154:157], v[110:113]
	v_mfma_f32_16x16x32_bf16 v[102:105], v[130:133], v[162:165], v[102:105]
	v_mfma_f32_16x16x32_bf16 v[94:97], v[138:141], v[162:165], v[94:97]
	v_mfma_f32_16x16x32_bf16 v[86:89], v[130:133], v[170:173], v[86:89]
	v_mfma_f32_16x16x32_bf16 v[78:81], v[138:141], v[170:173], v[78:81]
	v_mfma_f32_16x16x32_bf16 v[126:129], v[134:137], v[150:153], v[126:129]
	v_mfma_f32_16x16x32_bf16 v[122:125], v[142:145], v[150:153], v[122:125]
	v_mfma_f32_16x16x32_bf16 v[118:121], v[134:137], v[158:161], v[118:121]
	v_mfma_f32_16x16x32_bf16 v[110:113], v[142:145], v[158:161], v[110:113]
	v_mfma_f32_16x16x32_bf16 v[102:105], v[134:137], v[166:169], v[102:105]
	v_mfma_f32_16x16x32_bf16 v[94:97], v[142:145], v[166:169], v[94:97]
	v_mfma_f32_16x16x32_bf16 v[86:89], v[134:137], v[174:177], v[86:89]
	v_mfma_f32_16x16x32_bf16 v[78:81], v[142:145], v[174:177], v[78:81]
	s_waitcnt lgkmcnt(0)
	v_mfma_f32_16x16x32_bf16 v[114:117], v[202:205], v[146:149], v[114:117]
	v_mfma_f32_16x16x32_bf16 v[106:109], v[210:213], v[146:149], v[106:109]
	v_mfma_f32_16x16x32_bf16 v[98:101], v[202:205], v[154:157], v[98:101]
	v_mfma_f32_16x16x32_bf16 v[90:93], v[210:213], v[154:157], v[90:93]
	v_mfma_f32_16x16x32_bf16 v[82:85], v[202:205], v[162:165], v[82:85]
	v_mfma_f32_16x16x32_bf16 v[74:77], v[210:213], v[162:165], v[74:77]
	v_mfma_f32_16x16x32_bf16 v[70:73], v[202:205], v[170:173], v[70:73]
	v_mfma_f32_16x16x32_bf16 v[66:69], v[210:213], v[170:173], v[66:69]
	v_mfma_f32_16x16x32_bf16 v[114:117], v[206:209], v[150:153], v[114:117]
	v_mfma_f32_16x16x32_bf16 v[106:109], v[214:217], v[150:153], v[106:109]
	v_mfma_f32_16x16x32_bf16 v[98:101], v[206:209], v[158:161], v[98:101]
	v_mfma_f32_16x16x32_bf16 v[90:93], v[214:217], v[158:161], v[90:93]
	v_mfma_f32_16x16x32_bf16 v[82:85], v[206:209], v[166:169], v[82:85]
	v_mfma_f32_16x16x32_bf16 v[74:77], v[214:217], v[166:169], v[74:77]
	v_mfma_f32_16x16x32_bf16 v[70:73], v[206:209], v[174:177], v[70:73]
	v_mfma_f32_16x16x32_bf16 v[66:69], v[214:217], v[174:177], v[66:69]
	s_setprio 0
	s_barrier
	s_add_i32 m0, s65, 0x18000
	s_nop 0
	global_load_lds_dwordx4 v182, s[86:87]
	s_add_i32 m0, s65, 0x1a000
	s_nop 0
	global_load_lds_dwordx4 v186, s[86:87]
	s_mov_b32 m0, s70
	s_nop 0
	global_load_lds_dwordx4 v180, s[88:89]
	s_mov_b32 m0, s71
	s_nop 0
	global_load_lds_dwordx4 v184, s[88:89]
	ds_read_b128 v[146:149], v245 offset:49152
	ds_read_b128 v[150:153], v245 offset:50176
	ds_read_b128 v[154:157], v245 offset:51200
	ds_read_b128 v[158:161], v245 offset:52224
	ds_read_b128 v[162:165], v245 offset:53248
	ds_read_b128 v[166:169], v245 offset:54272
	ds_read_b128 v[170:173], v245 offset:55296
	ds_read_b128 v[174:177], v245 offset:56320
	s_cmp_ge_u32 s61, s72
	s_cbranch_scc1 .Lmy_q21_last
	s_waitcnt vmcnt(6)
	s_branch .Lmy_q21_cont
